# v3 + flat grid barrier: non-returning arrival on the group counter, one 8-lane sc1 poll of the 8 group counters
# baseline (speedup 1.0000x reference)
; __device__ __forceinline__ void grid_barrier(unsigned* bar, unsigned gen) {
;     asm volatile("s_waitcnt vmcnt(0) lgkmcnt(0)" ::: "memory");
;     __syncthreads();
;     if (threadIdx.x < 64) {
;         if (threadIdx.x == 0) {
;             const unsigned g = blockIdx.x & 7, G = gridDim.x, gsize = (G + 7 - g) >> 3, ng = G < 8 ? G : 8;
;             __builtin_amdgcn_fence(__ATOMIC_RELEASE, "agent");
;             asm volatile("s_waitcnt vmcnt(0)" ::: "memory");
;             if (__hip_atomic_fetch_add(bar + 64 * (1 + g), 1u, __ATOMIC_RELAXED, __HIP_MEMORY_SCOPE_AGENT) + 1 == gen * gsize) {
;                 if (__hip_atomic_fetch_add(bar, 1u, __ATOMIC_RELAXED, __HIP_MEMORY_SCOPE_AGENT) + 1 == gen * ng) {
;                     for (unsigned j = 0; j < ng; ++j) __hip_atomic_store(bar + 64 * (9 + j), gen, __ATOMIC_RELAXED, __HIP_MEMORY_SCOPE_AGENT);
;                 }
;             }
;             while (__hip_atomic_load(bar + 64 * (9 + g), __ATOMIC_RELAXED, __HIP_MEMORY_SCOPE_AGENT) < gen) __builtin_amdgcn_s_sleep(1);
;         }
;         __builtin_amdgcn_fence(__ATOMIC_ACQUIRE, "agent");
;         asm volatile("s_waitcnt vmcnt(0)" ::: "memory");
;     }
;     __syncthreads();
; }
.LBB0_131:
	v_readlane_b32 s2, v253, 2
	s_cmp_le_i32 s68, s2
	s_cselect_b64 s[4:5], -1, 0
	s_xor_b64 s[6:7], s[80:81], -1
	s_or_b64 s[4:5], s[4:5], s[6:7]
	s_and_b64 vcc, exec, s[4:5]
	v_readlane_b32 s3, v253, 3
	s_cbranch_vccnz .LBB0_160
	v_readlane_b32 s2, v253, 32
	v_readlane_b32 s3, v253, 33
	s_mov_b64 s[12:13], -1
	s_and_b64 vcc, exec, s[2:3]
	s_cbranch_vccz .LBB0_147
	s_waitcnt vmcnt(0) lgkmcnt(0)
	v_readlane_b32 s2, v253, 51
	s_add_i32 s4, s2, 1
	s_barrier
	s_mov_b64 s[12:13], exec
	v_readlane_b32 s6, v253, 52
	v_readlane_b32 s7, v253, 53
	s_and_b64 s[6:7], s[12:13], s[6:7]
	s_mov_b64 exec, s[6:7]
	s_cbranch_execz .LBB0_146
	s_load_dword s5, s[88:89], 0x0
	buffer_wbl2 sc1
	v_readlane_b32 s28, v253, 62
	v_readlane_b32 s29, v253, 63
	v_readlane_b32 s20, v253, 35
	v_readlane_b32 s21, v253, 36
	v_mov_b32_e32 v1, 1
	v_lshlrev_b32_e32 v0, 8, v183
	s_waitcnt lgkmcnt(0)
	s_waitcnt vmcnt(0)
	s_mov_b64 exec, 1
	global_atomic_add v97, v1, s[28:29] offset:256
	s_mov_b64 exec, 0xff
	v_sub_u32_e32 v1, s5, v183
	v_add_u32_e32 v1, 7, v1
	v_lshrrev_b32_e32 v1, 3, v1
	v_mul_lo_u32 v1, v1, s4
.Lgb_poll:
	global_load_dword v2, v0, s[20:21] offset:256 sc1
	s_waitcnt vmcnt(0)
	v_cmp_lt_u32_e32 vcc, v2, v1
	s_cbranch_vccz .Lgb_done
	s_sleep 1
	s_branch .Lgb_poll
.Lgb_done:
	s_mov_b64 exec, s[6:7]
	buffer_inv sc1
	s_waitcnt vmcnt(0)
